# + P3 mix-norm loop: gain loads hoisted as in the other RMSNorm loops
# baseline (speedup 1.0000x reference)
; __device__ __forceinline__ void rms_row2_bf16(const float* xa, const float* xb, const float* g, bf16_t* oa, bf16_t* ob, int lane) {
;     f32x4 va[8], vb[8]; float sa = 0.f, sb = 0.f;
; #pragma unroll
;     for (int j = 0; j < 8; ++j) { va[j] = __builtin_nontemporal_load((const f32x4*)xa + lane + 64 * j); vb[j] = __builtin_nontemporal_load((const f32x4*)xb + lane + 64 * j); }
; #pragma unroll
; __global__ void __launch_bounds__(NTHREADS, 2) fwd_kernel(Args args) {
;     ...
;         if (G == 256) {
;             const bool gb = (bid < 64) || (bid >= 192);
;             const int cb = gb ? (bid < 64 ? bid : bid - 128) : bid - 64, wv = cb * 8 + wave;
;             const int base = gb ? 24576 : 0, npair = gb ? 4 : 12;
;             for (int j = 0; j < npair; ++j) { const size_t r0 = (size_t)base + wv + (size_t)(2 * j) * 1024, r1 = r0 + 1024;
;                 rms_row2_bf16(out + r0 * D, out + r1 * D, mix_norm, XN + r0 * D, XN + r1 * D, lane); }
.LBB0_318:
	s_and_b64 vcc, exec, s[0:1]
	s_cbranch_vccz .LBB0_321
	v_mbcnt_lo_u32_b32 v0, -1, 0
	v_mbcnt_hi_u32_b32 v0, -1, v0
	v_and_b32_e32 v1, 64, v0
	v_add_u32_e32 v1, 64, v1
	v_xor_b32_e32 v2, 1, v0
	v_cmp_lt_i32_e32 vcc, v2, v1
	s_add_i32 s6, s83, 0xffffff40
	s_add_i32 s7, s83, 0xffffff80
	v_cndmask_b32_e32 v2, v0, v2, vcc
	v_lshlrev_b32_e32 v55, 2, v2
	v_xor_b32_e32 v2, 2, v0
	v_cmp_lt_i32_e32 vcc, v2, v1
	s_and_b64 s[0:1], s[4:5], exec
	s_cselect_b32 s0, s83, s7
	v_cndmask_b32_e32 v2, v0, v2, vcc
	v_lshlrev_b32_e32 v58, 2, v2
	v_xor_b32_e32 v2, 4, v0
	v_cmp_lt_i32_e32 vcc, v2, v1
	s_sub_i32 s1, s83, 64
	s_cmp_lt_u32 s6, 0xffffff80
	v_cndmask_b32_e32 v2, v0, v2, vcc
	v_lshlrev_b32_e32 v59, 2, v2
	v_xor_b32_e32 v2, 8, v0
	v_cmp_lt_i32_e32 vcc, v2, v1
	s_brev_b32 s4, 32
	s_cselect_b32 s0, s0, s1
	v_cndmask_b32_e32 v2, v0, v2, vcc
	v_lshlrev_b32_e32 v60, 2, v2
	v_xor_b32_e32 v2, 16, v0
	v_cmp_lt_i32_e32 vcc, v2, v1
	s_cselect_b32 s7, s4, 0xc000000
	s_cselect_b32 s4, 0x6000, 0
	v_cndmask_b32_e32 v2, v0, v2, vcc
	v_lshlrev_b32_e32 v61, 2, v2
	v_xor_b32_e32 v2, 32, v0
	s_lshl_b32 s0, s0, 3
	v_cmp_lt_i32_e32 vcc, v2, v1
	s_add_i32 s0, s82, s0
	v_readlane_b32 s8, v245, 3
	v_cndmask_b32_e32 v0, v0, v2, vcc
	s_ashr_i32 s1, s0, 31
	v_lshlrev_b32_e32 v62, 2, v0
	v_lshlrev_b32_e32 v0, 4, v176
	v_mov_b32_e32 v1, 0
	v_readlane_b32 s18, v245, 13
	v_readlane_b32 s19, v245, 14
	s_add_u32 s0, s4, s0
	s_mov_b64 s[4:5], 0x1000
	v_lshl_add_u64 v[40:41], s[18:19], 0, v[0:1]
	v_lshl_add_u64 v[42:43], v[40:41], 0, s[4:5]
	s_mov_b64 s[4:5], 0x1400
	v_lshl_add_u64 v[44:45], v[40:41], 0, s[4:5]
	s_mov_b64 s[4:5], 0x1800
	s_addc_u32 s1, 0, s1
	v_lshl_add_u64 v[46:47], v[40:41], 0, s[4:5]
	s_mov_b64 s[4:5], 0x1c00
	v_lshl_add_u64 v[48:49], v[40:41], 0, s[4:5]
	s_lshl_b64 s[4:5], s[0:1], 12
	s_add_u32 s4, s92, s4
	s_addc_u32 s5, s93, s5
	s_lshl_b64 s[0:1], s[0:1], 13
	v_lshlrev_b32_e32 v2, 3, v176
	v_mov_b32_e32 v3, v1
	s_add_u32 s0, s90, s0
	v_readlane_b32 s9, v245, 4
	v_readlane_b32 s10, v245, 5
	v_readlane_b32 s11, v245, 6
	v_lshl_add_u64 v[2:3], s[4:5], 0, v[2:3]
	s_mov_b64 s[4:5], 0xe200e00
	s_addc_u32 s1, s91, s1
	v_lshl_add_u64 v[50:51], v[2:3], 0, s[4:5]
	v_lshl_add_u64 v[52:53], s[0:1], 0, v[0:1]
	s_mov_b64 s[4:5], 0
	s_mov_b32 s8, 0x800000
	s_mov_b32 s6, 0x3a000000
	v_mov_b32_e32 v54, 0x358637bd
	s_mov_b32 s9, 0xffc00000
	s_mov_b64 s[10:11], 0x800000
	v_readlane_b32 s12, v245, 7
	v_readlane_b32 s13, v245, 8
	v_readlane_b32 s14, v245, 9
	v_readlane_b32 s15, v245, 10
	v_readlane_b32 s16, v245, 11
	v_readlane_b32 s17, v245, 12
	v_readlane_b32 s20, v245, 15
	v_readlane_b32 s21, v245, 16
	v_readlane_b32 s22, v245, 17
	v_readlane_b32 s23, v245, 18
	global_load_dwordx4 v[134:137], v[40:41], off
	global_load_dwordx4 v[138:141], v[40:41], off offset:1024
	global_load_dwordx4 v[142:145], v[40:41], off offset:2048
	global_load_dwordx4 v[146:149], v[40:41], off offset:3072
	global_load_dwordx4 v[150:153], v[42:43], off
	global_load_dwordx4 v[154:157], v[44:45], off
	global_load_dwordx4 v[158:161], v[46:47], off
	global_load_dwordx4 v[162:165], v[48:49], off
.LBB0_320:
	v_add_co_u32_e32 v56, vcc, s9, v50
	v_lshl_add_u64 v[4:5], v[52:53], 0, s[4:5]
	s_nop 0
	v_addc_co_u32_e32 v57, vcc, -1, v51, vcc
	global_load_dwordx4 v[68:71], v[4:5], off nt
	global_load_dwordx4 v[72:75], v[4:5], off offset:1024 nt
	global_load_dwordx4 v[76:79], v[4:5], off offset:2048 nt
	global_load_dwordx4 v[36:39], v[4:5], off offset:3072 nt
	v_add_co_u32_e32 v0, vcc, 0x800000, v4
	s_add_u32 s4, s4, 0x1000000
	s_nop 0
	v_addc_co_u32_e32 v1, vcc, 0, v5, vcc
	global_load_dwordx4 v[80:83], v[0:1], off nt
	global_load_dwordx4 v[84:87], v[0:1], off offset:1024 nt
	global_load_dwordx4 v[88:91], v[0:1], off offset:2048 nt
	global_load_dwordx4 v[32:35], v[0:1], off offset:3072 nt
	v_add_co_u32_e32 v6, vcc, 0x1000, v4
	s_addc_u32 s5, s5, 0
	s_nop 0
	v_addc_co_u32_e32 v7, vcc, 0, v5, vcc
	v_add_co_u32_e32 v8, vcc, 0x801000, v4
	global_load_dwordx4 v[28:31], v[6:7], off nt
	global_load_dwordx4 v[20:23], v[6:7], off offset:1024 nt
	global_load_dwordx4 v[0:3], v[6:7], off offset:3072 nt
	global_load_dwordx4 v[12:15], v[6:7], off offset:2048 nt
	v_addc_co_u32_e32 v9, vcc, 0, v5, vcc
	global_load_dwordx4 v[24:27], v[8:9], off nt
	global_load_dwordx4 v[16:19], v[8:9], off offset:1024 nt
	global_load_dwordx4 v[4:7], v[8:9], off offset:3072 nt
	s_nop 0
	global_load_dwordx4 v[8:11], v[8:9], off offset:2048 nt
	s_cmp_eq_u32 s7, s4
	s_waitcnt vmcnt(0)
; __device__ __forceinline__ float wave_sum(float v) {
; #pragma unroll
;     for (int o = 1; o < 64; o <<= 1) v += __shfl_xor(v, o);
;     return v;
; __device__ __forceinline__ void rms_row2_bf16(const float* xa, const float* xb, const float* g, bf16_t* oa, bf16_t* ob, int lane) {
;     ...
; #pragma unroll
;     for (int j = 0; j < 8; ++j) { sa += (va[j][0] * va[j][0] + va[j][1] * va[j][1]) + (va[j][2] * va[j][2] + va[j][3] * va[j][3]); sb += (vb[j][0] * vb[j][0] + vb[j][1] * vb[j][1]) + (vb[j][2] * vb[j][2] + vb[j][3] * vb[j][3]); }
;     const float ra = rsqrtf(wave_sum(sa) * (1.f / D) + EPS), rb = rsqrtf(wave_sum(sb) * (1.f / D) + EPS);
	v_mov_b32_e32 v94, v69
	v_mov_b32_e32 v95, v73
	v_mov_b32_e32 v98, v71
	v_mov_b32_e32 v99, v75
	v_mov_b32_e32 v92, v68
	v_mov_b32_e32 v93, v72
	v_mov_b32_e32 v96, v70
	v_mov_b32_e32 v97, v74
	v_pk_mul_f32 v[100:101], v[78:79], v[78:79]
	v_pk_mul_f32 v[102:103], v[76:77], v[76:77]
	v_pk_mul_f32 v[94:95], v[94:95], v[94:95]
	v_pk_mul_f32 v[98:99], v[98:99], v[98:99]
	v_mul_f32_e32 v104, v37, v37
	v_mul_f32_e32 v106, v39, v39
	v_pk_mov_b32 v[108:109], v[102:103], v[100:101] op_sel:[1,0]
	v_mov_b32_e32 v103, v101
	v_pk_fma_f32 v[92:93], v[92:93], v[92:93], v[94:95]
	v_pk_fma_f32 v[94:95], v[96:97], v[96:97], v[98:99]
	v_mov_b32_e32 v98, v81
	v_mov_b32_e32 v99, v85
	v_mov_b32_e32 v110, v83
	v_mov_b32_e32 v111, v87
	v_pk_fma_f32 v[100:101], v[36:37], v[36:37], v[104:105] op_sel_hi:[1,1,0]
	v_pk_fma_f32 v[104:105], v[38:39], v[38:39], v[106:107] op_sel_hi:[1,1,0]
	v_mov_b32_e32 v96, v80
	v_mov_b32_e32 v97, v84
	v_mov_b32_e32 v106, v82
	v_mov_b32_e32 v107, v86
	v_pk_add_f32 v[102:103], v[108:109], v[102:103]
	v_pk_mul_f32 v[108:109], v[90:91], v[90:91]
	v_pk_mul_f32 v[112:113], v[88:89], v[88:89]
	v_pk_add_f32 v[92:93], v[92:93], v[94:95]
	v_pk_mul_f32 v[94:95], v[98:99], v[98:99]
	v_pk_mul_f32 v[98:99], v[110:111], v[110:111]
	v_pk_mov_b32 v[110:111], v[112:113], v[108:109] op_sel:[1,0]
	v_mov_b32_e32 v113, v109
	v_pk_fma_f32 v[94:95], v[96:97], v[96:97], v[94:95]
	v_pk_fma_f32 v[96:97], v[106:107], v[106:107], v[98:99]
	v_mul_f32_e32 v114, v33, v33
	v_mul_f32_e32 v116, v35, v35
	v_pk_add_f32 v[98:99], v[110:111], v[112:113]
	v_pk_add_f32 v[94:95], v[94:95], v[96:97]
	v_mul_f32_e32 v63, v28, v28
	v_mul_f32_e32 v101, v29, v29
	v_mul_f32_e32 v105, v30, v30
	v_mul_f32_e32 v121, v31, v31
	v_pk_add_f32 v[102:103], v[102:103], v[102:103] op_sel:[0,1] op_sel_hi:[1,0]
	v_pk_fma_f32 v[108:109], v[32:33], v[32:33], v[114:115] op_sel_hi:[1,1,0]
	v_pk_fma_f32 v[114:115], v[34:35], v[34:35], v[116:117] op_sel_hi:[1,1,0]
	v_pk_add_f32 v[92:93], v[92:93], v[92:93] op_sel:[0,1] op_sel_hi:[1,0]
	v_mul_f32_e32 v128, v24, v24
	v_mul_f32_e32 v129, v25, v25
	v_pk_add_f32 v[98:99], v[98:99], v[98:99] op_sel:[0,1] op_sel_hi:[1,0]
	v_pk_add_f32 v[94:95], v[94:95], v[94:95] op_sel:[0,1] op_sel_hi:[1,0]
	v_pk_mul_f32 v[116:117], v[22:23], v[22:23]
	v_pk_mul_f32 v[118:119], v[20:21], v[20:21]
	v_mov_b32_e32 v103, v101
	v_mov_b32_e32 v101, v105
	v_mov_b32_e32 v105, v121
	v_mul_f32_e32 v109, v26, v26
	v_mul_f32_e32 v115, v27, v27
	v_pk_mul_f32 v[110:111], v[18:19], v[18:19]
	v_pk_mul_f32 v[112:113], v[16:17], v[16:17]
	v_mov_b32_e32 v93, v63
	v_mov_b32_e32 v99, v129
	v_mov_b32_e32 v95, v128
	v_mul_f32_e32 v123, v0, v0
	v_mul_f32_e32 v120, v13, v13
	v_mul_f32_e32 v122, v15, v15
	v_pk_mov_b32 v[106:107], v[118:119], v[116:117] op_sel:[1,0]
	v_mov_b32_e32 v119, v117
	v_pk_add_f32 v[96:97], v[100:101], v[104:105]
	v_pk_mov_b32 v[104:105], v[112:113], v[110:111] op_sel:[1,0]
	v_mov_b32_e32 v113, v111
	v_pk_add_f32 v[92:93], v[92:93], v[102:103]
	v_pk_add_f32 v[102:103], v[108:109], v[114:115]
	v_pk_add_f32 v[94:95], v[94:95], v[98:99]
	v_mul_f32_e32 v125, v1, v1
	v_pk_fma_f32 v[116:117], v[12:13], v[12:13], v[120:121] op_sel_hi:[1,1,0]
	v_pk_fma_f32 v[120:121], v[14:15], v[14:15], v[122:123] op_sel_hi:[1,1,0]
	v_mul_f32_e32 v122, v9, v9
	v_mul_f32_e32 v124, v11, v11
	v_pk_add_f32 v[100:101], v[106:107], v[118:119]
	v_pk_add_f32 v[104:105], v[104:105], v[112:113]
	v_pk_add_f32 v[92:93], v[92:93], v[96:97]
	v_pk_add_f32 v[94:95], v[94:95], v[102:103]
	v_mul_f32_e32 v126, v2, v2
	v_mul_f32_e32 v127, v3, v3
	v_mul_f32_e32 v130, v4, v4
	v_mul_f32_e32 v131, v5, v5
	v_mul_f32_e32 v132, v6, v6
	v_mul_f32_e32 v133, v7, v7
	v_pk_fma_f32 v[106:107], v[8:9], v[8:9], v[122:123] op_sel_hi:[1,1,0]
	v_pk_fma_f32 v[110:111], v[10:11], v[10:11], v[124:125] op_sel_hi:[1,1,0]
	v_pk_add_f32 v[100:101], v[100:101], v[100:101] op_sel:[0,1] op_sel_hi:[1,0]
	v_pk_add_f32 v[96:97], v[104:105], v[104:105] op_sel:[0,1] op_sel_hi:[1,0]
	v_pk_add_f32 v[92:93], v[92:93], v[92:93] op_sel:[0,1] op_sel_hi:[1,0]
	v_pk_add_f32 v[94:95], v[94:95], v[94:95] op_sel:[0,1] op_sel_hi:[1,0]
	v_mov_b32_e32 v117, v126
	v_mov_b32_e32 v121, v127
	v_mov_b32_e32 v107, v132
	v_mov_b32_e32 v111, v133
	v_mov_b32_e32 v101, v125
	v_mov_b32_e32 v97, v131
	v_mov_b32_e32 v93, v123
	v_mov_b32_e32 v95, v130
	v_pk_add_f32 v[108:109], v[116:117], v[120:121]
	v_pk_add_f32 v[104:105], v[106:107], v[110:111]
	v_pk_add_f32 v[92:93], v[92:93], v[100:101]
	v_pk_add_f32 v[94:95], v[94:95], v[96:97]
	v_pk_add_f32 v[92:93], v[92:93], v[108:109]
	v_pk_add_f32 v[94:95], v[94:95], v[104:105]
	v_mov_b32_e32 v97, v92
	v_mov_b32_e32 v96, v94
	v_mov_b32_e32 v92, v95
	v_pk_add_f32 v[92:93], v[96:97], v[92:93]
	ds_bpermute_b32 v95, v55, v93
	ds_bpermute_b32 v94, v55, v92
	s_waitcnt lgkmcnt(0)
	v_pk_add_f32 v[92:93], v[92:93], v[94:95]
	ds_bpermute_b32 v95, v58, v93
	ds_bpermute_b32 v94, v58, v92
	s_waitcnt lgkmcnt(0)
	v_pk_add_f32 v[92:93], v[92:93], v[94:95]
	ds_bpermute_b32 v95, v59, v93
	ds_bpermute_b32 v94, v59, v92
	s_waitcnt lgkmcnt(0)
	v_pk_add_f32 v[92:93], v[92:93], v[94:95]
	ds_bpermute_b32 v95, v60, v93
	ds_bpermute_b32 v94, v60, v92
	s_waitcnt lgkmcnt(0)
	v_pk_add_f32 v[92:93], v[92:93], v[94:95]
	ds_bpermute_b32 v95, v61, v93
	ds_bpermute_b32 v94, v61, v92
	s_waitcnt lgkmcnt(0)
	v_pk_add_f32 v[92:93], v[92:93], v[94:95]
	ds_bpermute_b32 v95, v62, v93
	ds_bpermute_b32 v94, v62, v92
	s_waitcnt lgkmcnt(0)
; __device__ __forceinline__ unsigned cvt_pk_bf16(float lo, float hi) { f32x2_c v = {lo, hi}; bf16x2_c r = __builtin_convertvector(v, bf16x2_c); return __builtin_bit_cast(unsigned, r); }
; __device__ __forceinline__ void rms_row2_bf16(const float* xa, const float* xb, const float* g, bf16_t* oa, bf16_t* ob, int lane) {
;     ...
;     const float ra = rsqrtf(wave_sum(sa) * (1.f / D) + EPS), rb = rsqrtf(wave_sum(sb) * (1.f / D) + EPS);
; #pragma unroll
;     for (int j = 0; j < 8; ++j) { const f32x4 gg = ((const f32x4*)g)[lane + 64 * j]; u32x2 o;
;         o.x = cvt_pk_bf16(va[j][0] * ra * gg[0], va[j][1] * ra * gg[1]); o.y = cvt_pk_bf16(va[j][2] * ra * gg[2], va[j][3] * ra * gg[3]); __builtin_nontemporal_store(o, (u32x2*)oa + lane + 64 * j);
;         o.x = cvt_pk_bf16(vb[j][0] * rb * gg[0], vb[j][1] * rb * gg[1]); o.y = cvt_pk_bf16(vb[j][2] * rb * gg[2], vb[j][3] * rb * gg[3]); __builtin_nontemporal_store(o, (u32x2*)ob + lane + 64 * j); }
	v_pk_add_f32 v[92:93], v[92:93], v[94:95]
	s_nop 0
	v_pk_fma_f32 v[92:93], v[92:93], s[6:7], v[54:55] op_sel_hi:[1,0,0]
	s_nop 0
	v_mul_f32_e32 v63, 0x4b800000, v93
	v_cmp_gt_f32_e64 s[0:1], s8, v93
	v_mul_f32_e32 v94, 0x4b800000, v92
	v_cmp_gt_f32_e32 vcc, s8, v92
	v_cndmask_b32_e64 v63, v93, v63, s[0:1]
	v_rsq_f32_e32 v63, v63
	v_cndmask_b32_e32 v92, v92, v94, vcc
	v_rsq_f32_e32 v93, v92
	v_mul_f32_e32 v92, 0x45800000, v63
	v_cndmask_b32_e64 v92, v63, v92, s[0:1]
	v_mul_f32_e32 v94, 0x45800000, v93
	v_cndmask_b32_e32 v94, v93, v94, vcc
	v_pk_mul_f32 v[68:69], v[68:69], v[92:93] op_sel_hi:[1,0]
	v_pk_mul_f32 v[70:71], v[70:71], v[92:93] op_sel_hi:[1,0]
	v_pk_mul_f32 v[80:81], v[80:81], v[94:95] op_sel_hi:[1,0]
	v_pk_mul_f32 v[82:83], v[82:83], v[94:95] op_sel_hi:[1,0]
	v_pk_mul_f32 v[68:69], v[134:135], v[68:69]
	v_pk_mul_f32 v[70:71], v[136:137], v[70:71]
	v_pk_mul_f32 v[64:65], v[134:135], v[80:81]
	v_pk_mul_f32 v[66:67], v[136:137], v[82:83]
	v_cvt_pk_bf16_f32 v68, v68, v69
	v_cvt_pk_bf16_f32 v69, v70, v71
	v_cvt_pk_bf16_f32 v64, v64, v65
	v_cvt_pk_bf16_f32 v65, v66, v67
	global_store_dwordx2 v[56:57], v[68:69], off offset:-3584 nt
	global_store_dwordx2 v[50:51], v[64:65], off offset:-3584 nt
	v_pk_mul_f32 v[68:69], v[72:73], v[92:93] op_sel_hi:[1,0]
	v_pk_mul_f32 v[70:71], v[74:75], v[92:93] op_sel_hi:[1,0]
	v_pk_mul_f32 v[72:73], v[84:85], v[94:95] op_sel_hi:[1,0]
	v_pk_mul_f32 v[74:75], v[86:87], v[94:95] op_sel_hi:[1,0]
	v_pk_mul_f32 v[36:37], v[36:37], v[92:93] op_sel_hi:[1,0]
	v_pk_mul_f32 v[38:39], v[38:39], v[92:93] op_sel_hi:[1,0]
	v_pk_mul_f32 v[32:33], v[32:33], v[94:95] op_sel_hi:[1,0]
	v_pk_mul_f32 v[34:35], v[34:35], v[94:95] op_sel_hi:[1,0]
	v_pk_mul_f32 v[28:29], v[28:29], v[92:93] op_sel_hi:[1,0]
	v_pk_mul_f32 v[30:31], v[30:31], v[92:93] op_sel_hi:[1,0]
	v_pk_mul_f32 v[24:25], v[24:25], v[94:95] op_sel_hi:[1,0]
	v_pk_mul_f32 v[26:27], v[26:27], v[94:95] op_sel_hi:[1,0]
	v_pk_mul_f32 v[20:21], v[20:21], v[92:93] op_sel_hi:[1,0]
	v_pk_mul_f32 v[22:23], v[22:23], v[92:93] op_sel_hi:[1,0]
	v_pk_mul_f32 v[16:17], v[16:17], v[94:95] op_sel_hi:[1,0]
	v_pk_mul_f32 v[18:19], v[18:19], v[94:95] op_sel_hi:[1,0]
	v_pk_mul_f32 v[12:13], v[12:13], v[92:93] op_sel_hi:[1,0]
	v_pk_mul_f32 v[14:15], v[14:15], v[92:93] op_sel_hi:[1,0]
	v_pk_mul_f32 v[8:9], v[8:9], v[94:95] op_sel_hi:[1,0]
	v_pk_mul_f32 v[10:11], v[10:11], v[94:95] op_sel_hi:[1,0]
	v_pk_mul_f32 v[0:1], v[0:1], v[92:93] op_sel_hi:[1,0]
	v_pk_mul_f32 v[2:3], v[2:3], v[92:93] op_sel_hi:[1,0]
	v_pk_mul_f32 v[4:5], v[4:5], v[94:95] op_sel_hi:[1,0]
	v_pk_mul_f32 v[6:7], v[6:7], v[94:95] op_sel_hi:[1,0]
	v_pk_mul_f32 v[68:69], v[68:69], v[138:139]
	v_pk_mul_f32 v[70:71], v[70:71], v[140:141]
	v_pk_mul_f32 v[64:65], v[138:139], v[72:73]
	v_pk_mul_f32 v[66:67], v[140:141], v[74:75]
	v_cvt_pk_bf16_f32 v68, v68, v69
	v_cvt_pk_bf16_f32 v69, v70, v71
	v_cvt_pk_bf16_f32 v64, v64, v65
	v_cvt_pk_bf16_f32 v65, v66, v67
	global_store_dwordx2 v[56:57], v[68:69], off offset:-3072 nt
	global_store_dwordx2 v[50:51], v[64:65], off offset:-3072 nt
	v_pk_mul_f32 v[68:69], v[76:77], v[92:93] op_sel_hi:[1,0]
	v_pk_mul_f32 v[70:71], v[78:79], v[92:93] op_sel_hi:[1,0]
	v_pk_mul_f32 v[72:73], v[88:89], v[94:95] op_sel_hi:[1,0]
	v_pk_mul_f32 v[74:75], v[90:91], v[94:95] op_sel_hi:[1,0]
	v_pk_mul_f32 v[68:69], v[68:69], v[142:143]
	v_pk_mul_f32 v[70:71], v[70:71], v[144:145]
	v_pk_mul_f32 v[64:65], v[142:143], v[72:73]
	v_pk_mul_f32 v[66:67], v[144:145], v[74:75]
	v_cvt_pk_bf16_f32 v68, v68, v69
	v_cvt_pk_bf16_f32 v69, v70, v71
	v_cvt_pk_bf16_f32 v64, v64, v65
	v_cvt_pk_bf16_f32 v65, v66, v67
	global_store_dwordx2 v[56:57], v[68:69], off offset:-2560 nt
	global_store_dwordx2 v[50:51], v[64:65], off offset:-2560 nt
	v_pk_mul_f32 v[36:37], v[36:37], v[146:147]
	v_pk_mul_f32 v[38:39], v[38:39], v[148:149]
	v_pk_mul_f32 v[32:33], v[32:33], v[146:147]
	v_pk_mul_f32 v[34:35], v[34:35], v[148:149]
	v_cvt_pk_bf16_f32 v36, v36, v37
	v_cvt_pk_bf16_f32 v37, v38, v39
	v_cvt_pk_bf16_f32 v32, v32, v33
	v_cvt_pk_bf16_f32 v33, v34, v35
	global_store_dwordx2 v[56:57], v[36:37], off offset:-2048 nt
	global_store_dwordx2 v[50:51], v[32:33], off offset:-2048 nt
	v_pk_mul_f32 v[28:29], v[28:29], v[150:151]
	v_pk_mul_f32 v[30:31], v[30:31], v[152:153]
	v_pk_mul_f32 v[24:25], v[24:25], v[150:151]
	v_pk_mul_f32 v[26:27], v[26:27], v[152:153]
	v_cvt_pk_bf16_f32 v28, v28, v29
	v_cvt_pk_bf16_f32 v29, v30, v31
	v_cvt_pk_bf16_f32 v24, v24, v25
	v_cvt_pk_bf16_f32 v25, v26, v27
	global_store_dwordx2 v[56:57], v[28:29], off offset:-1536 nt
	global_store_dwordx2 v[50:51], v[24:25], off offset:-1536 nt
	v_pk_mul_f32 v[20:21], v[20:21], v[154:155]
	v_pk_mul_f32 v[22:23], v[22:23], v[156:157]
	v_pk_mul_f32 v[16:17], v[16:17], v[154:155]
	v_pk_mul_f32 v[18:19], v[18:19], v[156:157]
	v_cvt_pk_bf16_f32 v20, v20, v21
	v_cvt_pk_bf16_f32 v21, v22, v23
	v_cvt_pk_bf16_f32 v16, v16, v17
	v_cvt_pk_bf16_f32 v17, v18, v19
	global_store_dwordx2 v[56:57], v[20:21], off offset:-1024 nt
	global_store_dwordx2 v[50:51], v[16:17], off offset:-1024 nt
	v_pk_mul_f32 v[12:13], v[12:13], v[158:159]
	v_pk_mul_f32 v[14:15], v[14:15], v[160:161]
	v_pk_mul_f32 v[8:9], v[8:9], v[158:159]
	v_pk_mul_f32 v[10:11], v[10:11], v[160:161]
	v_cvt_pk_bf16_f32 v12, v12, v13
	v_cvt_pk_bf16_f32 v13, v14, v15
	v_cvt_pk_bf16_f32 v8, v8, v9
	v_cvt_pk_bf16_f32 v9, v10, v11
	global_store_dwordx2 v[56:57], v[12:13], off offset:-512 nt
	global_store_dwordx2 v[50:51], v[8:9], off offset:-512 nt
	v_pk_mul_f32 v[0:1], v[0:1], v[162:163]
	v_pk_mul_f32 v[2:3], v[2:3], v[164:165]
	v_pk_mul_f32 v[4:5], v[4:5], v[162:163]
	v_pk_mul_f32 v[6:7], v[6:7], v[164:165]
	v_cvt_pk_bf16_f32 v0, v0, v1
	v_cvt_pk_bf16_f32 v1, v2, v3
	v_cvt_pk_bf16_f32 v2, v4, v5
	v_cvt_pk_bf16_f32 v3, v6, v7
	global_store_dwordx2 v[56:57], v[0:1], off nt
	global_store_dwordx2 v[50:51], v[2:3], off nt
	v_lshl_add_u64 v[50:51], v[50:51], 0, s[10:11]
	s_cbranch_scc0 .LBB0_320
